# swa_finalize token loop: q/k row loads issued at the top of the iteration with the gate-input load; gate mat-vec LDS row reads kept 8 in flight
# speedup vs baseline: 1.0943x; 1.0025x over previous
; DI void swa_finalize(const P& p, char* smem, int vb, int nvb) {
;     ...
;   for (int t = vb * 4 + wave; t < T; t += nvb * 4) {
;     if (lane < 32) sds[lane] = side[(size_t)t * 32 + lane];
;     wave_lds_sync();
;     ...
;       uint4 v = *(const uint4*)(z + (size_t)t * ODD_IN + 1568 + lane * 8);
;       unpack8(v, f);
;       float ss = 0.f;
; #pragma unroll
;       for (int j = 0; j < 8; ++j) ss += f[j] * f[j];
;       ss += __shfl_xor(ss, 1); ss += __shfl_xor(ss, 2); ss += __shfl_xor(ss, 4);
;       const float rms = rsqrtf(ss * (1.f / 64.f) + EPS);
; #pragma unroll
;       for (int j = 0; j < 8; ++j) {
;         const float yv = f[j] * rms * qn[j];
;         const float pv = __shfl_xor(yv, 4);
;         const float o = (sub < 4) ? (yv * cj[j] - pv * sj[j]) : (pv * sj[j] + yv * cj[j]);
;         f[j] = o * SSCALE;
;       }
;       *(uint4*)(Q + (size_t)t * 512 + lane * 8) = pack8(f);
;     }
;     {
;       const int l16 = lane & 15;
;       uint4 v = *(const uint4*)(z + (size_t)t * ODD_IN + 2080 + l16 * 8);
.LBB0_601:
	v_lshl_add_u64 v[84:85], s[70:71], 0, v[34:35]
	v_add_co_u32_e32 v84, vcc, 0x5872000, v84
	s_nop 1
	v_addc_co_u32_e32 v85, vcc, 0, v85, vcc
	global_load_dwordx4 v[74:77], v[84:85], off offset:3136
	v_lshl_add_u64 v[84:85], s[70:71], 0, v[36:37]
	v_add_co_u32_e32 v84, vcc, 0x5873000, v84
	s_nop 1
	v_addc_co_u32_e32 v85, vcc, 0, v85, vcc
	global_load_dwordx4 v[78:81], v[84:85], off offset:64
	s_and_saveexec_b64 s[4:5], s[0:1]
	s_cbranch_execz .LBB0_603
	v_lshl_add_u64 v[16:17], s[70:71], 0, v[30:31]
	global_load_dword v16, v[16:17], off
	s_waitcnt vmcnt(0)
	ds_write_b32 v55, v16 offset:34816

; DI void swa_finalize(const P& p, char* smem, int vb, int nvb) {
;     ...
;     float cj[8], sj[8];
; #pragma unroll
;     for (int j = 0; j < 8; ++j) { cj[j] = __shfl(cs, (sub & 3) * 8 + j); sj[j] = __shfl(sn, (sub & 3) * 8 + j); }
;     float f[8];
;     if (lat) {
;       uint4 v = *(const uint4*)(z + (size_t)t * ODD_IN + 1568 + lane * 8);
;       unpack8(v, f);
;       float ss = 0.f;
; #pragma unroll
;       for (int j = 0; j < 8; ++j) ss += f[j] * f[j];
;       ss += __shfl_xor(ss, 1); ss += __shfl_xor(ss, 2); ss += __shfl_xor(ss, 4);
;       const float rms = rsqrtf(ss * (1.f / 64.f) + EPS);
; #pragma unroll
;       for (int j = 0; j < 8; ++j) {
;         const float yv = f[j] * rms * qn[j];
;         const float pv = __shfl_xor(yv, 4);
;         const float o = (sub < 4) ? (yv * cj[j] - pv * sj[j]) : (pv * sj[j] + yv * cj[j]);
;         f[j] = o * SSCALE;
;       }
;       *(uint4*)(Q + (size_t)t * 512 + lane * 8) = pack8(f);
.LBB0_605:
	s_or_b64 exec, exec, s[4:5]
	v_mbcnt_hi_u32_b32 v59, -1, v135
	v_and_or_b32 v17, v59, 64, v58
	v_lshlrev_b32_e32 v17, 2, v17
	ds_bpermute_b32 v44, v17, v16
	ds_bpermute_b32 v45, v17, v29
	ds_bpermute_b32 v42, v17, v16 offset:4
	ds_bpermute_b32 v43, v17, v29 offset:4
	ds_bpermute_b32 v26, v17, v16 offset:8
	ds_bpermute_b32 v27, v17, v29 offset:8
	ds_bpermute_b32 v24, v17, v16 offset:12
	ds_bpermute_b32 v25, v17, v29 offset:12
	ds_bpermute_b32 v22, v17, v16 offset:16
	ds_bpermute_b32 v23, v17, v29 offset:16
	ds_bpermute_b32 v20, v17, v16 offset:20
	ds_bpermute_b32 v21, v17, v29 offset:20
	ds_bpermute_b32 v18, v17, v16 offset:24
	ds_bpermute_b32 v19, v17, v29 offset:24
	v_or_b32_e32 v17, 28, v17
	ds_bpermute_b32 v16, v17, v16
	ds_bpermute_b32 v17, v17, v29
	v_and_b32_e32 v46, 64, v59
	v_xor_b32_e32 v51, 1, v59
	v_add_u32_e32 v29, 64, v46
	v_xor_b32_e32 v61, 2, v59
	v_xor_b32_e32 v60, 4, v59
	s_and_saveexec_b64 s[4:5], vcc
	s_xor_b64 s[4:5], exec, s[4:5]
	v_xor_b32_e32 v51, 1, v59
	v_add_u32_e32 v29, 64, v46
	v_xor_b32_e32 v61, 2, v59
	v_xor_b32_e32 v60, 4, v59
	s_andn2_saveexec_b64 s[4:5], s[4:5]
	s_cbranch_execz .LBB0_609
	v_lshl_add_u64 v[46:47], s[70:71], 0, v[34:35]
	v_add_co_u32_e32 v46, vcc, 0x5872000, v46
	s_mov_b32 s16, 0x3e38aa3b
	s_nop 0
	v_addc_co_u32_e32 v47, vcc, 0, v47, vcc
	v_cmp_lt_i32_e32 vcc, v51, v29
	s_waitcnt vmcnt(2)
	v_lshlrev_b32_e32 v66, 16, v74
	v_and_b32_e32 v67, 0xffff0000, v74
	v_lshlrev_b32_e32 v52, 16, v75
	v_and_b32_e32 v53, 0xffff0000, v75
	v_pk_mul_f32 v[70:71], v[66:67], v[66:67]
	v_pk_mul_f32 v[68:69], v[52:53], v[52:53]
	v_add_f32_e32 v70, v70, v71
	v_lshlrev_b32_e32 v48, 16, v76
	v_and_b32_e32 v49, 0xffff0000, v76
	v_cndmask_b32_e32 v50, v59, v51, vcc
	v_cmp_lt_i32_e32 vcc, v61, v29
	v_add_f32_e32 v68, v70, v68
	v_lshlrev_b32_e32 v46, 16, v77
	v_and_b32_e32 v47, 0xffff0000, v77
	v_cndmask_b32_e32 v62, v59, v61, vcc
	v_cmp_lt_i32_e32 vcc, v60, v29
	v_pk_mul_f32 v[64:65], v[48:49], v[48:49]
	v_add_f32_e32 v68, v69, v68
	v_lshlrev_b32_e32 v72, 2, v62
	v_cndmask_b32_e32 v62, v59, v60, vcc
	v_add_f32_e32 v64, v64, v68
	v_lshlrev_b32_e32 v73, 2, v62
	v_pk_mul_f32 v[62:63], v[46:47], v[46:47]
	v_add_f32_e32 v64, v65, v64
	v_add_f32_e32 v62, v62, v64
	v_lshlrev_b32_e32 v50, 2, v50
	v_add_f32_e32 v62, v63, v62
	ds_bpermute_b32 v50, v50, v62
	s_waitcnt lgkmcnt(14)
	v_mov_b32_e32 v68, v45
	s_waitcnt lgkmcnt(13)
	v_mov_b32_e32 v69, v43
	s_waitcnt lgkmcnt(0)
	v_add_f32_e32 v50, v62, v50
	ds_bpermute_b32 v62, v72, v50
	s_waitcnt lgkmcnt(0)
	v_add_f32_e32 v50, v50, v62
	ds_bpermute_b32 v62, v73, v50
	s_waitcnt lgkmcnt(0)
	v_add_f32_e32 v50, v50, v62
	v_fmamk_f32 v50, v50, 0x3c800000, v119
	v_cmp_gt_f32_e32 vcc, s9, v50
	v_mul_f32_e32 v62, 0x4b800000, v50
	s_nop 0
	v_cndmask_b32_e32 v50, v50, v62, vcc
	v_rsq_f32_e32 v50, v50
	s_nop 0
	v_mul_f32_e32 v62, 0x45800000, v50
	v_cndmask_b32_e32 v50, v50, v62, vcc
	v_pk_mul_f32 v[62:63], v[50:51], v[66:67] op_sel_hi:[0,1]
	v_pk_mul_f32 v[62:63], v[12:13], v[62:63]
	ds_bpermute_b32 v64, v73, v62
	ds_bpermute_b32 v65, v73, v63
	v_pk_mul_f32 v[52:53], v[50:51], v[52:53] op_sel_hi:[0,1]
	v_mov_b32_e32 v66, v44
	v_mov_b32_e32 v67, v42
	v_pk_mul_f32 v[52:53], v[14:15], v[52:53]
	s_waitcnt lgkmcnt(0)
	v_pk_mul_f32 v[64:65], v[68:69], v[64:65]
	v_mov_b32_e32 v68, v27
	v_cndmask_b32_e64 v65, v65, -v65, s[78:79]
	v_cndmask_b32_e64 v64, v64, -v64, s[78:79]
	v_pk_fma_f32 v[62:63], v[62:63], v[66:67], v[64:65]
	ds_bpermute_b32 v64, v73, v52
	ds_bpermute_b32 v65, v73, v53
	v_mov_b32_e32 v69, v25
	v_pk_mul_f32 v[48:49], v[50:51], v[48:49] op_sel_hi:[0,1]
	v_mov_b32_e32 v66, v26
	v_mov_b32_e32 v67, v24
	s_waitcnt lgkmcnt(0)
	v_pk_mul_f32 v[64:65], v[68:69], v[64:65]
	v_pk_mul_f32 v[48:49], v[4:5], v[48:49]
	v_cndmask_b32_e64 v65, v65, -v65, s[78:79]
	v_cndmask_b32_e64 v64, v64, -v64, s[78:79]
	v_pk_fma_f32 v[52:53], v[52:53], v[66:67], v[64:65]
	ds_bpermute_b32 v64, v73, v48
	ds_bpermute_b32 v65, v73, v49
	v_mov_b32_e32 v68, v23
	v_mov_b32_e32 v69, v21
	v_pk_mul_f32 v[46:47], v[50:51], v[46:47] op_sel_hi:[0,1]
	v_mov_b32_e32 v66, v22
	s_waitcnt lgkmcnt(0)
	v_pk_mul_f32 v[64:65], v[68:69], v[64:65]
	v_mov_b32_e32 v67, v20
	v_cndmask_b32_e64 v65, v65, -v65, s[78:79]
	v_cndmask_b32_e64 v64, v64, -v64, s[78:79]
	v_pk_mul_f32 v[46:47], v[6:7], v[46:47]
	v_pk_fma_f32 v[48:49], v[48:49], v[66:67], v[64:65]
	ds_bpermute_b32 v64, v73, v46
	ds_bpermute_b32 v65, v73, v47
	v_mov_b32_e32 v68, v19
	v_mov_b32_e32 v69, v17
	v_mov_b32_e32 v66, v18
	v_mov_b32_e32 v67, v16
	s_waitcnt lgkmcnt(0)
	v_pk_mul_f32 v[64:65], v[68:69], v[64:65]
	v_pk_mul_f32 v[62:63], v[62:63], s[16:17] op_sel_hi:[1,0]
	v_cndmask_b32_e64 v65, v65, -v65, s[78:79]
	v_cndmask_b32_e64 v64, v64, -v64, s[78:79]
	v_pk_fma_f32 v[46:47], v[46:47], v[66:67], v[64:65]
	v_pk_mul_f32 v[52:53], v[52:53], s[16:17] op_sel_hi:[1,0]
	v_pk_mul_f32 v[48:49], v[48:49], s[16:17] op_sel_hi:[1,0]
	v_pk_mul_f32 v[64:65], v[46:47], s[16:17] op_sel_hi:[1,0]
	v_add_co_u32_e32 v40, vcc, 0xbb72000, v40
	v_cvt_pk_bf16_f32 v46, v62, v63
	v_cvt_pk_bf16_f32 v47, v52, v53
	v_cvt_pk_bf16_f32 v48, v48, v49
	v_cvt_pk_bf16_f32 v49, v64, v65
	v_addc_co_u32_e32 v41, vcc, 0, v41, vcc
	global_store_dwordx4 v[40:41], v[46:49], off
; DI void swa_finalize(const P& p, char* smem, int vb, int nvb) {
;     ...
;     {
;       const int l16 = lane & 15;
;       uint4 v = *(const uint4*)(z + (size_t)t * ODD_IN + 2080 + l16 * 8);
;       unpack8(v, f);
;       float ss = 0.f;
; #pragma unroll
;       for (int j = 0; j < 8; ++j) ss += f[j] * f[j];
;       ss += __shfl_xor(ss, 1); ss += __shfl_xor(ss, 2); ss += __shfl_xor(ss, 4);
;       const float rms = rsqrtf(ss * (1.f / 64.f) + EPS);
; #pragma unroll
;       for (int j = 0; j < 8; ++j) {
;         const float yv = f[j] * rms * kn[j];
;         const float pv = __shfl_xor(yv, 4);
;         float o = yv;
;         if (lat) o = (sub < 4) ? (yv * cj[j] - pv * sj[j]) : (pv * sj[j] + yv * cj[j]);
;         f[j] = o;
;       }
;       if (lane < 16) *(uint4*)(Kb + (size_t)t * 128 + lane * 8) = pack8(f);
.LBB0_609:
	s_or_b64 exec, exec, s[4:5]
	v_lshl_add_u64 v[40:41], s[70:71], 0, v[36:37]
	v_add_co_u32_e32 v40, vcc, 0x5873000, v40
	s_nop 1
	v_addc_co_u32_e32 v41, vcc, 0, v41, vcc
	v_cmp_lt_i32_e32 vcc, v51, v29
	s_waitcnt vmcnt(3)
	v_lshlrev_b32_e32 v52, 16, v78
	v_cndmask_b32_e32 v40, v59, v51, vcc
	v_and_b32_e32 v53, 0xffff0000, v78
	v_lshlrev_b32_e32 v68, 2, v40
	v_lshlrev_b32_e32 v51, 16, v79
	v_and_b32_e32 v50, 0xffff0000, v79
	v_pk_mul_f32 v[40:41], v[52:53], v[52:53]
	v_pk_mul_f32 v[62:63], v[50:51], v[50:51]
	v_add_f32_e32 v40, v40, v41
	v_lshlrev_b32_e32 v49, 16, v80
	v_and_b32_e32 v48, 0xffff0000, v80
	v_add_f32_e32 v40, v40, v63
	v_lshlrev_b32_e32 v47, 16, v81
	v_and_b32_e32 v46, 0xffff0000, v81
	v_pk_mul_f32 v[64:65], v[48:49], v[48:49]
	v_add_f32_e32 v40, v62, v40
	v_add_f32_e32 v40, v65, v40
	v_pk_mul_f32 v[66:67], v[46:47], v[46:47]
	v_add_f32_e32 v40, v64, v40
	v_add_f32_e32 v40, v67, v40
	v_add_f32_e32 v40, v66, v40
	ds_bpermute_b32 v41, v68, v40
	v_cmp_lt_i32_e32 vcc, v61, v29
	s_waitcnt lgkmcnt(0)
	v_add_f32_e32 v40, v40, v41
	v_cndmask_b32_e32 v61, v59, v61, vcc
	v_lshlrev_b32_e32 v61, 2, v61
	ds_bpermute_b32 v41, v61, v40
	v_cmp_lt_i32_e32 vcc, v60, v29
	s_waitcnt lgkmcnt(0)
	v_add_f32_e32 v40, v40, v41
	v_cndmask_b32_e32 v29, v59, v60, vcc
	v_lshlrev_b32_e32 v29, 2, v29
	ds_bpermute_b32 v41, v29, v40
	s_waitcnt lgkmcnt(0)
	v_add_f32_e32 v40, v40, v41
	v_fmamk_f32 v40, v40, 0x3c800000, v119
	v_mul_f32_e32 v41, 0x4b800000, v40
	v_cmp_gt_f32_e32 vcc, s9, v40
	s_nop 1
	v_cndmask_b32_e32 v40, v40, v41, vcc
	v_rsq_f32_e32 v40, v40
	s_nop 0
	v_mul_f32_e32 v41, 0x45800000, v40
	v_cndmask_b32_e32 v59, v40, v41, vcc
	v_mul_f32_e32 v40, v59, v52
	v_mul_f32_e32 v40, v8, v40
	ds_bpermute_b32 v41, v29, v40
	s_and_saveexec_b64 s[4:5], s[38:39]
	s_cbranch_execz .LBB0_615
	s_and_saveexec_b64 s[16:17], s[76:77]
	s_xor_b64 s[44:45], exec, s[16:17]
	s_cbranch_execz .LBB0_612
	s_waitcnt lgkmcnt(0)
	v_pk_mul_f32 v[40:41], v[40:41], v[44:45]
	s_nop 0
	v_add_f32_e32 v40, v41, v40
